# modulation GEMV inner block: 36 scalar fmacs per 4 k instead of operand shuffles + packed fma
# baseline (speedup 1.0000x reference)
; __device__ __forceinline__ void prologue_a(const Args& a, LAS unsigned char* lds, int tid, int G) {
;     ...
;         for (int it = blockIdx.x; it < DEPTH * 72; it += G) {
;             const int l = it / 72, cb = it % 72, col = cb * 128 + jj;
;             const float* wp = a.in[I_WMOD] + (size_t)l * DM * 9216 + col;
;             float acc[9];
; #pragma unroll
;             for (int m = 0; m < 9; ++m) acc[m] = 0.f;
; #pragma unroll 4
;             for (int k = kq * 256; k < kq * 256 + 256; ++k) {
;                 const float w = __builtin_nontemporal_load(wp + (size_t)k * 9216);
; #pragma unroll
;                 for (int m = 0; m < 9; ++m) acc[m] += sc[m * 1024 + k] * w;
;             }
; #pragma unroll
;             for (int m = 0; m < 9; ++m) red[(kq * 9 + m) * 128 + jj] = acc[m];
.LBB0_62:
	v_lshl_add_u64 v[110:111], v[6:7], 0, s[10:11]
	global_load_dword v78, v[110:111], off nt
	v_lshl_add_u64 v[112:113], v[110:111], 0, s[0:1]
	global_load_dword v80, v[112:113], off nt
	v_lshl_add_u64 v[114:115], v[112:113], 0, s[0:1]
	global_load_dword v82, v[114:115], off nt
	v_lshl_add_u64 v[116:117], v[114:115], 0, s[0:1]
	global_load_dword v84, v[116:117], off nt
	v_lshl_add_u64 v[110:111], v[116:117], 0, s[0:1]
	global_load_dword v86, v[110:111], off nt
	v_lshl_add_u64 v[112:113], v[110:111], 0, s[0:1]
	global_load_dword v88, v[112:113], off nt
	v_lshl_add_u64 v[114:115], v[112:113], 0, s[0:1]
	global_load_dword v90, v[114:115], off nt
	v_lshl_add_u64 v[116:117], v[114:115], 0, s[0:1]
	global_load_dword v92, v[116:117], off nt
	v_lshl_add_u64 v[110:111], v[116:117], 0, s[0:1]
	global_load_dword v94, v[110:111], off nt
	v_lshl_add_u64 v[112:113], v[110:111], 0, s[0:1]
	global_load_dword v96, v[112:113], off nt
	v_lshl_add_u64 v[114:115], v[112:113], 0, s[0:1]
	global_load_dword v98, v[114:115], off nt
	v_lshl_add_u64 v[116:117], v[114:115], 0, s[0:1]
	global_load_dword v100, v[116:117], off nt
	v_lshl_add_u64 v[110:111], v[116:117], 0, s[0:1]
	global_load_dword v102, v[110:111], off nt
	v_lshl_add_u64 v[112:113], v[110:111], 0, s[0:1]
	global_load_dword v104, v[112:113], off nt
	v_lshl_add_u64 v[114:115], v[112:113], 0, s[0:1]
	global_load_dword v106, v[114:115], off nt
	v_lshl_add_u64 v[116:117], v[114:115], 0, s[0:1]
	global_load_dword v108, v[116:117], off nt
	s_add_u32 s10, s10, 0x90000
	s_addc_u32 s11, s11, 0
	ds_read_b128 v[22:25], v20 offset:4096
	ds_read_b128 v[26:29], v20 offset:8192
	ds_read_b128 v[30:33], v20 offset:12288
	ds_read_b128 v[34:37], v20 offset:16384
	ds_read_b128 v[40:43], v20 offset:20480
	ds_read_b128 v[44:47], v20 offset:24576
	ds_read_b128 v[48:51], v20 offset:28672
	ds_read_b128 v[52:55], v20
	ds_read_b128 v[56:59], v20 offset:32768
	s_waitcnt lgkmcnt(0)
	v_add_u32_e32 v20, 16, v20
	s_waitcnt vmcnt(15)
	v_fmac_f32_e32 v8, v78, v52
	v_fmac_f32_e32 v9, v78, v22
	v_fmac_f32_e32 v10, v78, v26
	v_fmac_f32_e32 v11, v78, v30
	v_fmac_f32_e32 v12, v78, v34
	v_fmac_f32_e32 v13, v78, v40
	v_fmac_f32_e32 v14, v78, v44
	v_fmac_f32_e32 v15, v78, v48
	v_fmac_f32_e32 v21, v78, v56
	s_waitcnt vmcnt(14)
	v_fmac_f32_e32 v8, v80, v53
	v_fmac_f32_e32 v9, v80, v23
	v_fmac_f32_e32 v10, v80, v27
	v_fmac_f32_e32 v11, v80, v31
	v_fmac_f32_e32 v12, v80, v35
	v_fmac_f32_e32 v13, v80, v41
	v_fmac_f32_e32 v14, v80, v45
	v_fmac_f32_e32 v15, v80, v49
	v_fmac_f32_e32 v21, v80, v57
	s_waitcnt vmcnt(13)
	v_fmac_f32_e32 v8, v82, v54
	v_fmac_f32_e32 v9, v82, v24
	v_fmac_f32_e32 v10, v82, v28
	v_fmac_f32_e32 v11, v82, v32
	v_fmac_f32_e32 v12, v82, v36
	v_fmac_f32_e32 v13, v82, v42
	v_fmac_f32_e32 v14, v82, v46
	v_fmac_f32_e32 v15, v82, v50
	v_fmac_f32_e32 v21, v82, v58
	s_waitcnt vmcnt(12)
	v_fmac_f32_e32 v8, v84, v55
	v_fmac_f32_e32 v9, v84, v25
	v_fmac_f32_e32 v10, v84, v29
	v_fmac_f32_e32 v11, v84, v33
	v_fmac_f32_e32 v12, v84, v37
	v_fmac_f32_e32 v13, v84, v43
	v_fmac_f32_e32 v14, v84, v47
	v_fmac_f32_e32 v15, v84, v51
	v_fmac_f32_e32 v21, v84, v59
	ds_read_b128 v[22:25], v20 offset:4096
	ds_read_b128 v[26:29], v20 offset:8192
	ds_read_b128 v[30:33], v20 offset:12288
	ds_read_b128 v[34:37], v20 offset:16384
	ds_read_b128 v[40:43], v20 offset:20480
	ds_read_b128 v[44:47], v20 offset:24576
	ds_read_b128 v[48:51], v20 offset:28672
	ds_read_b128 v[52:55], v20
	ds_read_b128 v[56:59], v20 offset:32768
	s_waitcnt lgkmcnt(0)
	v_add_u32_e32 v20, 16, v20
	s_waitcnt vmcnt(11)
	v_fmac_f32_e32 v8, v86, v52
	v_fmac_f32_e32 v9, v86, v22
	v_fmac_f32_e32 v10, v86, v26
	v_fmac_f32_e32 v11, v86, v30
	v_fmac_f32_e32 v12, v86, v34
	v_fmac_f32_e32 v13, v86, v40
	v_fmac_f32_e32 v14, v86, v44
	v_fmac_f32_e32 v15, v86, v48
	v_fmac_f32_e32 v21, v86, v56
	s_waitcnt vmcnt(10)
	v_fmac_f32_e32 v8, v88, v53
	v_fmac_f32_e32 v9, v88, v23
	v_fmac_f32_e32 v10, v88, v27
	v_fmac_f32_e32 v11, v88, v31
	v_fmac_f32_e32 v12, v88, v35
	v_fmac_f32_e32 v13, v88, v41
	v_fmac_f32_e32 v14, v88, v45
	v_fmac_f32_e32 v15, v88, v49
	v_fmac_f32_e32 v21, v88, v57
	s_waitcnt vmcnt(9)
	v_fmac_f32_e32 v8, v90, v54
	v_fmac_f32_e32 v9, v90, v24
	v_fmac_f32_e32 v10, v90, v28
	v_fmac_f32_e32 v11, v90, v32
	v_fmac_f32_e32 v12, v90, v36
	v_fmac_f32_e32 v13, v90, v42
	v_fmac_f32_e32 v14, v90, v46
	v_fmac_f32_e32 v15, v90, v50
	v_fmac_f32_e32 v21, v90, v58
	s_waitcnt vmcnt(8)
; __device__ __forceinline__ void prologue_a(const Args& a, LAS unsigned char* lds, int tid, int G) {
;     ...
; #pragma unroll 4
;             for (int k = kq * 256; k < kq * 256 + 256; ++k) {
;                 const float w = __builtin_nontemporal_load(wp + (size_t)k * 9216);
; #pragma unroll
;                 for (int m = 0; m < 9; ++m) acc[m] += sc[m * 1024 + k] * w;
;             }
; #pragma unroll
;             for (int m = 0; m < 9; ++m) red[(kq * 9 + m) * 128 + jj] = acc[m];
;             __syncthreads();
;             for (int o = tid; o < 9 * 128; o += 512) { const int m = o >> 7, j2 = o & 127;
;                 const float v = red[(0 * 9 + m) * 128 + j2] + red[(1 * 9 + m) * 128 + j2] + red[(2 * 9 + m) * 128 + j2] + red[(3 * 9 + m) * 128 + j2];
;                 MOD[((size_t)l * 9 + m) * 9216 + cb * 128 + j2] = v + a.in[I_BMOD][l * 9216 + cb * 128 + j2]; }
	v_fmac_f32_e32 v8, v92, v55
	v_fmac_f32_e32 v9, v92, v25
	v_fmac_f32_e32 v10, v92, v29
	v_fmac_f32_e32 v11, v92, v33
	v_fmac_f32_e32 v12, v92, v37
	v_fmac_f32_e32 v13, v92, v43
	v_fmac_f32_e32 v14, v92, v47
	v_fmac_f32_e32 v15, v92, v51
	v_fmac_f32_e32 v21, v92, v59
	ds_read_b128 v[22:25], v20 offset:4096
	ds_read_b128 v[26:29], v20 offset:8192
	ds_read_b128 v[30:33], v20 offset:12288
	ds_read_b128 v[34:37], v20 offset:16384
	ds_read_b128 v[40:43], v20 offset:20480
	ds_read_b128 v[44:47], v20 offset:24576
	ds_read_b128 v[48:51], v20 offset:28672
	ds_read_b128 v[52:55], v20
	ds_read_b128 v[56:59], v20 offset:32768
	s_waitcnt lgkmcnt(0)
	v_add_u32_e32 v20, 16, v20
	s_waitcnt vmcnt(7)
	v_fmac_f32_e32 v8, v94, v52
	v_fmac_f32_e32 v9, v94, v22
	v_fmac_f32_e32 v10, v94, v26
	v_fmac_f32_e32 v11, v94, v30
	v_fmac_f32_e32 v12, v94, v34
	v_fmac_f32_e32 v13, v94, v40
	v_fmac_f32_e32 v14, v94, v44
	v_fmac_f32_e32 v15, v94, v48
	v_fmac_f32_e32 v21, v94, v56
	s_waitcnt vmcnt(6)
	v_fmac_f32_e32 v8, v96, v53
	v_fmac_f32_e32 v9, v96, v23
	v_fmac_f32_e32 v10, v96, v27
	v_fmac_f32_e32 v11, v96, v31
	v_fmac_f32_e32 v12, v96, v35
	v_fmac_f32_e32 v13, v96, v41
	v_fmac_f32_e32 v14, v96, v45
	v_fmac_f32_e32 v15, v96, v49
	v_fmac_f32_e32 v21, v96, v57
	s_waitcnt vmcnt(5)
	v_fmac_f32_e32 v8, v98, v54
	v_fmac_f32_e32 v9, v98, v24
	v_fmac_f32_e32 v10, v98, v28
	v_fmac_f32_e32 v11, v98, v32
	v_fmac_f32_e32 v12, v98, v36
	v_fmac_f32_e32 v13, v98, v42
	v_fmac_f32_e32 v14, v98, v46
	v_fmac_f32_e32 v15, v98, v50
	v_fmac_f32_e32 v21, v98, v58
	s_waitcnt vmcnt(4)
	v_fmac_f32_e32 v8, v100, v55
	v_fmac_f32_e32 v9, v100, v25
	v_fmac_f32_e32 v10, v100, v29
	v_fmac_f32_e32 v11, v100, v33
	v_fmac_f32_e32 v12, v100, v37
	v_fmac_f32_e32 v13, v100, v43
	v_fmac_f32_e32 v14, v100, v47
	v_fmac_f32_e32 v15, v100, v51
	v_fmac_f32_e32 v21, v100, v59
	ds_read_b128 v[22:25], v20 offset:4096
	ds_read_b128 v[26:29], v20 offset:8192
	ds_read_b128 v[30:33], v20 offset:12288
	ds_read_b128 v[34:37], v20 offset:16384
	ds_read_b128 v[40:43], v20 offset:20480
	ds_read_b128 v[44:47], v20 offset:24576
	ds_read_b128 v[48:51], v20 offset:28672
	ds_read_b128 v[52:55], v20
	ds_read_b128 v[56:59], v20 offset:32768
	s_waitcnt lgkmcnt(0)
	v_add_u32_e32 v20, 16, v20
	s_waitcnt vmcnt(3)
	v_fmac_f32_e32 v8, v102, v52
	v_fmac_f32_e32 v9, v102, v22
	v_fmac_f32_e32 v10, v102, v26
	v_fmac_f32_e32 v11, v102, v30
	v_fmac_f32_e32 v12, v102, v34
	v_fmac_f32_e32 v13, v102, v40
	v_fmac_f32_e32 v14, v102, v44
	v_fmac_f32_e32 v15, v102, v48
	v_fmac_f32_e32 v21, v102, v56
	s_waitcnt vmcnt(2)
	v_fmac_f32_e32 v8, v104, v53
	v_fmac_f32_e32 v9, v104, v23
	v_fmac_f32_e32 v10, v104, v27
	v_fmac_f32_e32 v11, v104, v31
	v_fmac_f32_e32 v12, v104, v35
	v_fmac_f32_e32 v13, v104, v41
	v_fmac_f32_e32 v14, v104, v45
	v_fmac_f32_e32 v15, v104, v49
	v_fmac_f32_e32 v21, v104, v57
	s_waitcnt vmcnt(1)
	v_fmac_f32_e32 v8, v106, v54
	v_fmac_f32_e32 v9, v106, v24
	v_fmac_f32_e32 v10, v106, v28
	v_fmac_f32_e32 v11, v106, v32
	v_fmac_f32_e32 v12, v106, v36
	v_fmac_f32_e32 v13, v106, v42
	v_fmac_f32_e32 v14, v106, v46
	v_fmac_f32_e32 v15, v106, v50
	v_fmac_f32_e32 v21, v106, v58
	s_waitcnt vmcnt(0)
	v_fmac_f32_e32 v8, v108, v55
	v_fmac_f32_e32 v9, v108, v25
	v_fmac_f32_e32 v10, v108, v29
	v_fmac_f32_e32 v11, v108, v33
	v_fmac_f32_e32 v12, v108, v37
	v_fmac_f32_e32 v13, v108, v43
	v_fmac_f32_e32 v14, v108, v47
	v_fmac_f32_e32 v15, v108, v51
	v_fmac_f32_e32 v21, v108, v59
	s_cmp_eq_u32 s10, 0x900000
	s_cbranch_scc0 .LBB0_62
	ds_write2st64_b32 v19, v8, v9 offset0:144 offset1:146
	ds_write2st64_b32 v19, v10, v11 offset0:148 offset1:150
	ds_write2st64_b32 v19, v12, v13 offset0:152 offset1:154
	ds_write2st64_b32 v19, v14, v15 offset0:156 offset1:158
	ds_write_b32 v19, v21 offset:40960
	s_waitcnt lgkmcnt(0)
	s_barrier
	s_and_saveexec_b64 s[10:11], vcc
	s_cbranch_execz .LBB0_60
	s_mul_i32 s0, s9, 0x2400
	s_add_i32 s0, s0, s8
	v_or_b32_e32 v6, s0, v16
	s_mul_hi_i32 s13, s9, 9
	s_mul_i32 s12, s9, 9
	s_ashr_i32 s9, s8, 31
	v_ashrrev_i32_e32 v7, 31, v6
	v_lshl_add_u64 v[6:7], v[6:7], 2, s[86:87]
	v_lshl_add_u64 v[8:9], s[8:9], 2, v[2:3]
	s_mov_b64 s[8:9], 0
	v_mov_b32_e32 v10, v18
	v_mov_b32_e32 v11, v158
